# baseline (speedup 1.0000x reference)
; #define LAS __attribute__((address_space(3)))
; __device__ __forceinline__ void xattn_fast(const Ctx& C) {
;     ...
;     const int per = C.G >> 4;
;     if (per == 0) return;
;     const int bhx = C.bid / per, sub = C.bid % per;
;     if (bhx >= 16) return;
;     const int b = bhx >> 2, h = bhx & 3;
;     {
;         const bf16* ks = WSP(const bf16, WS_XK) + (size_t)bhx * 256 * 128;
;         const bf16* vs = WSP(const bf16, WS_XVT) + (size_t)bhx * 128 * 256;
; #pragma unroll
;         for (int i = 0; i < 8; ++i) {
;             const int chunk = tid + 512 * i;
;             { const int row = chunk >> 4, cc = chunk & 15; *(LAS u32x4*)(lds + row * XK_PITCH + cc * 16) = *(const u32x4*)(ks + row * 128 + cc * 8); }
;             { const int row = chunk >> 5, cc = chunk & 31; *(LAS u32x4*)(lds + XV_OFF + row * XV_PITCH + cc * 16) = *(const u32x4*)(vs + row * 256 + cc * 8); }
;         }
;     }
;     __syncthreads();
;     const float* gq = C.in[22];
;     const int ntile = SEQ / 32;
;     for (int wt = sub * 8 + wave; wt < ntile; wt += per * 8) {
.LBB0_813:
	s_or_b64 exec, exec, s[0:1]
	s_cmp_lt_u32 s42, 16
	s_waitcnt lgkmcnt(0)
	s_barrier
	s_cbranch_scc1 .LBB0_820
	s_ashr_i32 s4, s42, 4
	s_abs_i32 s0, s4
	v_cvt_f32_u32_e32 v0, s0
	s_sub_i32 s6, 0, s0
	s_abs_i32 s1, s33
	s_xor_b32 s5, s33, s4
	v_rcp_iflag_f32_e32 v0, v0
	s_ashr_i32 s5, s5, 31
	v_mul_f32_e32 v0, 0x4f7ffffe, v0
	v_cvt_u32_f32_e32 v0, v0
	s_nop 0
	v_readfirstlane_b32 s7, v0
	s_mul_i32 s6, s6, s7
	s_mul_hi_u32 s6, s7, s6
	s_add_i32 s7, s7, s6
	s_mul_hi_u32 s6, s1, s7
	s_mul_i32 s7, s6, s0
	s_sub_i32 s1, s1, s7
	s_add_i32 s8, s6, 1
	s_sub_i32 s7, s1, s0
	s_cmp_ge_u32 s1, s0
	s_cselect_b32 s6, s8, s6
	s_cselect_b32 s1, s7, s1
	s_add_i32 s7, s6, 1
	s_cmp_ge_u32 s1, s0
	s_cselect_b32 s0, s7, s6
	s_xor_b32 s0, s0, s5
	s_sub_i32 s0, s0, s5
	s_cmp_gt_i32 s0, 15
	s_cbranch_scc1 .LBB0_820
	s_mul_i32 s1, s0, s4
	s_sub_i32 s5, s33, s1
	s_ashr_i32 s1, s0, 31
	s_lshl_b64 s[6:7], s[0:1], 16
	s_add_u32 s6, s78, s6
	s_addc_u32 s7, s79, s7
	v_lshlrev_b32_e32 v0, 4, v188
	v_mov_b32_e32 v1, 0
	v_lshl_add_u64 v[2:3], s[6:7], 0, v[0:1]
	s_mov_b64 s[8:9], 0x1a200000
	v_add_u32_e32 v66, 0, v0
	v_lshlrev_b32_e32 v0, 4, v201
	s_add_i32 s1, 0, 0x11000
	v_lshl_add_u64 v[58:59], v[2:3], 0, s[8:9]
	v_lshl_add_u64 v[2:3], s[6:7], 0, v[0:1]
	s_mov_b64 s[6:7], 0x1a300000
	v_add_u32_e32 v67, s1, v0
	v_lshlrev_b32_e32 v0, 8, v200
	v_lshl_add_u64 v[62:63], v[2:3], 0, s[6:7]
	v_lshl_add_u64 v[10:11], v[58:59], 0, v[0:1]
	v_lshlrev_b32_e32 v0, 9, v199
	v_lshl_add_u64 v[12:13], v[62:63], 0, v[0:1]
	global_load_dwordx4 v[2:5], v[10:11], off
	global_load_dwordx4 v[6:9], v[12:13], off
	v_add_u32_e32 v10, 0x200, v182
	v_lshrrev_b32_e32 v68, 4, v10
	v_lshlrev_b32_e32 v0, 8, v68
	v_lshrrev_b32_e32 v69, 5, v10
	v_lshl_add_u64 v[18:19], v[58:59], 0, v[0:1]
	v_lshlrev_b32_e32 v0, 9, v69
	v_lshl_add_u64 v[20:21], v[62:63], 0, v[0:1]
	global_load_dwordx4 v[10:13], v[18:19], off
	global_load_dwordx4 v[14:17], v[20:21], off
	v_or_b32_e32 v18, 0x400, v182
	v_lshrrev_b32_e32 v70, 4, v18
	v_lshlrev_b32_e32 v0, 8, v70
	v_lshrrev_b32_e32 v71, 5, v18
	v_lshl_add_u64 v[26:27], v[58:59], 0, v[0:1]
	v_lshlrev_b32_e32 v0, 9, v71
	v_lshl_add_u64 v[28:29], v[62:63], 0, v[0:1]
	global_load_dwordx4 v[18:21], v[26:27], off
	global_load_dwordx4 v[22:25], v[28:29], off
	v_add_u32_e32 v26, 0x600, v182
	v_lshrrev_b32_e32 v72, 4, v26
	v_lshlrev_b32_e32 v0, 8, v72
	v_lshrrev_b32_e32 v73, 5, v26
	v_lshl_add_u64 v[34:35], v[58:59], 0, v[0:1]
	v_lshlrev_b32_e32 v0, 9, v73
	v_lshl_add_u64 v[36:37], v[62:63], 0, v[0:1]
	global_load_dwordx4 v[26:29], v[34:35], off
	global_load_dwordx4 v[30:33], v[36:37], off
	v_or_b32_e32 v34, 0x800, v182
	v_lshrrev_b32_e32 v74, 4, v34
	v_lshlrev_b32_e32 v0, 8, v74
	v_lshrrev_b32_e32 v75, 5, v34
	v_lshl_add_u64 v[42:43], v[58:59], 0, v[0:1]
	v_lshlrev_b32_e32 v0, 9, v75
	v_lshl_add_u64 v[44:45], v[62:63], 0, v[0:1]
	global_load_dwordx4 v[34:37], v[42:43], off
	global_load_dwordx4 v[38:41], v[44:45], off
	v_add_u32_e32 v42, 0xa00, v182
	v_lshrrev_b32_e32 v76, 4, v42
	v_lshlrev_b32_e32 v0, 8, v76
	v_lshrrev_b32_e32 v77, 5, v42
	v_lshl_add_u64 v[50:51], v[58:59], 0, v[0:1]
	v_lshlrev_b32_e32 v0, 9, v77
	v_lshl_add_u64 v[52:53], v[62:63], 0, v[0:1]
	global_load_dwordx4 v[42:45], v[50:51], off
	global_load_dwordx4 v[46:49], v[52:53], off
	v_or_b32_e32 v50, 0xc00, v182
	v_lshrrev_b32_e32 v78, 4, v50
	v_lshlrev_b32_e32 v0, 8, v78
	v_lshrrev_b32_e32 v79, 5, v50
	v_lshl_add_u64 v[60:61], v[58:59], 0, v[0:1]
	v_lshlrev_b32_e32 v0, 9, v79
	v_lshl_add_u64 v[64:65], v[62:63], 0, v[0:1]
	global_load_dwordx4 v[50:53], v[60:61], off
	global_load_dwordx4 v[54:57], v[64:65], off
	v_add_u32_e32 v64, 0xe00, v182
	v_lshrrev_b32_e32 v80, 4, v64
	v_lshlrev_b32_e32 v0, 8, v80
	v_lshl_add_u64 v[58:59], v[58:59], 0, v[0:1]
	global_load_dwordx4 v[58:61], v[58:59], off
	v_lshrrev_b32_e32 v81, 5, v64
	v_lshlrev_b32_e32 v0, 9, v81
	v_lshl_add_u64 v[62:63], v[62:63], 0, v[0:1]
	global_load_dwordx4 v[62:65], v[62:63], off
	s_movk_i32 s6, 0x110
	v_mad_u32_u24 v0, v200, s6, v66
	s_movk_i32 s1, 0x210
	s_waitcnt vmcnt(15)
	ds_write_b128 v0, v[2:5]
	v_mad_u32_u24 v0, v199, s1, v67
	s_waitcnt vmcnt(14)
	ds_write_b128 v0, v[6:9]
	v_mad_u32_u24 v0, v68, s6, v66
	s_waitcnt vmcnt(13)
	ds_write_b128 v0, v[10:13]
	v_mad_u32_u24 v0, v69, s1, v67
	s_waitcnt vmcnt(12)
	ds_write_b128 v0, v[14:17]
	v_mad_u32_u24 v0, v70, s6, v66
	s_waitcnt vmcnt(11)
	ds_write_b128 v0, v[18:21]
	v_mad_u32_u24 v0, v71, s1, v67
	s_waitcnt vmcnt(10)
	ds_write_b128 v0, v[22:25]
	v_mad_u32_u24 v0, v72, s6, v66
	s_waitcnt vmcnt(9)
	ds_write_b128 v0, v[26:29]
	v_mad_u32_u24 v0, v73, s1, v67
	s_waitcnt vmcnt(8)
	ds_write_b128 v0, v[30:33]
	v_mad_u32_u24 v0, v74, s6, v66
	s_waitcnt vmcnt(7)
	ds_write_b128 v0, v[34:37]
	v_mad_u32_u24 v0, v75, s1, v67
	s_waitcnt vmcnt(6)
	ds_write_b128 v0, v[38:41]
	v_mad_u32_u24 v0, v76, s6, v66
	s_waitcnt vmcnt(5)
	ds_write_b128 v0, v[42:45]
	v_mad_u32_u24 v0, v77, s1, v67
	s_waitcnt vmcnt(4)
	ds_write_b128 v0, v[46:49]
	v_mad_u32_u24 v0, v78, s6, v66
	s_waitcnt vmcnt(3)
	ds_write_b128 v0, v[50:53]
	v_mad_u32_u24 v0, v79, s1, v67
	s_waitcnt vmcnt(2)
	ds_write_b128 v0, v[54:57]
	v_mad_u32_u24 v0, v80, s6, v66
	s_waitcnt vmcnt(1)
	ds_write_b128 v0, v[58:61]
	v_mad_u32_u24 v0, v81, s1, v67
	s_lshl_b32 s1, s5, 3
	s_add_i32 s1, s1, s90
	s_cmpk_gt_i32 s1, 0xff
	s_waitcnt vmcnt(0)
	ds_write_b128 v0, v[62:65]
	s_waitcnt lgkmcnt(0)
	s_barrier
	s_cbranch_scc1 .LBB0_820
	s_lshl_b32 s5, s0, 11
	s_lshl_b32 s0, s0, 8
	s_and_b32 s5, s5, 0xffffe000
	s_lshl_b32 s4, s4, 3
	s_and_b32 s0, s0, 0x300
	v_lshrrev_b32_e32 v4, 5, v196
	v_and_b32_e32 v2, 32, v196
	v_mov_b32_e32 v3, v1
	s_add_u32 s8, s14, s0
	v_lshl_add_u64 v[152:153], s[56:57], 0, v[2:3]
	v_lshlrev_b32_e32 v2, 4, v4
	s_addc_u32 s9, s15, 0
	v_lshl_add_u64 v[154:155], s[8:9], 0, v[2:3]
	s_add_u32 s8, s78, s0
	v_lshlrev_b32_e32 v0, 3, v4
	s_addc_u32 s9, s79, 0
	v_mul_u32_u24_e32 v6, 0x210, v201
	v_lshl_add_u64 v[4:5], s[8:9], 0, v[0:1]
	s_mov_b64 s[8:9], 0x16000000
	v_or_b32_e32 v137, s5, v201
	v_lshl_add_u64 v[156:157], v[4:5], 0, s[8:9]
	v_or_b32_e32 v139, v6, v0
	v_mad_u32_u24 v141, v201, s6, v2
	v_mov_b32_e32 v143, 0x358637bd
	s_mov_b32 s0, 0x800000
	v_readfirstlane_b32 s5, v182
	s_nop 3
	s_lshr_b32 s5, s5, 6
	s_cmp_lt_u32 s5, 4
	s_cbranch_scc1 .Lstag_xa
	s_sleep 12
; __device__ __forceinline__ void xattn_fast(const Ctx& C) {
;     ...
;         const int tk = b * SEQ + wt * 32 + l32;
;         bf16x8 qf[8];
;         {
;             const bf16* qp = WSP(const bf16, WS_QX) + (size_t)tk * 512 + 128 * h + 8 * hf;
;             float ss = 0.f;
;             u32x4 raw[8];
; #pragma unroll
;             for (int kk = 0; kk < 8; ++kk) { raw[kk] = *(const u32x4*)(qp + 16 * kk);
;                 const float a0 = bflo(raw[kk].x), a1 = bfhi(raw[kk].x), a2 = bflo(raw[kk].y), a3 = bfhi(raw[kk].y), a4 = bflo(raw[kk].z), a5 = bfhi(raw[kk].z), a6 = bflo(raw[kk].w), a7 = bfhi(raw[kk].w);
;                 ss += (a0 * a0 + a1 * a1) + (a2 * a2 + a3 * a3) + (a4 * a4 + a5 * a5) + (a6 * a6 + a7 * a7); }
;             { auto rr = __builtin_amdgcn_permlane32_swap(__float_as_uint(ss), __float_as_uint(ss), false, false); ss = __uint_as_float(rr[0]) + __uint_as_float(rr[1]); }
;             const float rq = rsqrtf(ss * (1.f / 128.f) + EPS) * XSCALE;
.Lstag_xa:
.LBB0_817:
	v_lshl_add_u32 v80, s1, 5, v137
	v_ashrrev_i32_e32 v81, 31, v80
	v_lshlrev_b64 v[0:1], 10, v[80:81]
	v_lshl_add_u64 v[56:57], v[154:155], 0, v[0:1]
	global_load_dwordx4 v[64:67], v[56:57], off offset:224
	global_load_dwordx4 v[72:75], v[56:57], off offset:192
	global_load_dwordx4 v[82:85], v[56:57], off offset:160
	global_load_dwordx4 v[90:93], v[56:57], off offset:128
	global_load_dwordx4 v[96:99], v[56:57], off offset:96
	global_load_dwordx4 v[100:103], v[56:57], off offset:64
	global_load_dwordx4 v[48:51], v[152:153], off offset:16
	global_load_dwordx4 v[52:55], v[152:153], off
	global_load_dwordx4 v[40:43], v[152:153], off offset:80
	global_load_dwordx4 v[44:47], v[152:153], off offset:64
	global_load_dwordx4 v[32:35], v[152:153], off offset:144
	global_load_dwordx4 v[36:39], v[152:153], off offset:128
	global_load_dwordx4 v[24:27], v[152:153], off offset:208
	global_load_dwordx4 v[28:31], v[152:153], off offset:192
	global_load_dwordx4 v[16:19], v[152:153], off offset:272
	global_load_dwordx4 v[20:23], v[152:153], off offset:256
	global_load_dwordx4 v[8:11], v[152:153], off offset:336
	global_load_dwordx4 v[12:15], v[152:153], off offset:320
	global_load_dwordx4 v[0:3], v[152:153], off offset:400
	global_load_dwordx4 v[4:7], v[152:153], off offset:384
	global_load_dwordx4 v[104:107], v[56:57], off
	global_load_dwordx4 v[108:111], v[56:57], off offset:32
	v_mov_b32_e32 v149, 0xf149f2ca
	v_mov_b32_e32 v145, v141
	v_mov_b32_e32 v147, v139
	s_mov_b32 s5, 4
	s_waitcnt vmcnt(21)
	v_lshlrev_b32_e32 v60, 16, v65
	v_and_b32_e32 v61, 0xffff0000, v65
	v_lshlrev_b32_e32 v62, 16, v64
	v_and_b32_e32 v63, 0xffff0000, v64
	s_waitcnt vmcnt(20)
	v_lshlrev_b32_e32 v64, 16, v75
	v_and_b32_e32 v65, 0xffff0000, v75
	v_lshlrev_b32_e32 v68, 16, v73
	v_and_b32_e32 v69, 0xffff0000, v73
	s_waitcnt vmcnt(19)
	v_and_b32_e32 v73, 0xffff0000, v85
	v_and_b32_e32 v75, 0xffff0000, v84
	v_and_b32_e32 v77, 0xffff0000, v83
	v_and_b32_e32 v79, 0xffff0000, v82
	v_lshlrev_b32_e32 v56, 16, v67
	v_and_b32_e32 v57, 0xffff0000, v67
	v_lshlrev_b32_e32 v58, 16, v66
	v_and_b32_e32 v59, 0xffff0000, v66
	v_lshlrev_b32_e32 v66, 16, v74
	v_and_b32_e32 v67, 0xffff0000, v74
	v_lshlrev_b32_e32 v70, 16, v72
	v_and_b32_e32 v71, 0xffff0000, v72
	v_lshlrev_b32_e32 v72, 16, v85
	v_lshlrev_b32_e32 v74, 16, v84
	v_lshlrev_b32_e32 v76, 16, v83
	v_lshlrev_b32_e32 v78, 16, v82
	v_mov_b32_e32 v120, v73
	v_mov_b32_e32 v121, v75
	v_mov_b32_e32 v124, v79
	v_mov_b32_e32 v125, v77
	v_mov_b32_e32 v118, v72
	v_mov_b32_e32 v119, v74
	v_mov_b32_e32 v122, v78
	v_mov_b32_e32 v123, v76
	v_pk_mul_f32 v[120:121], v[120:121], v[120:121]
	v_pk_mul_f32 v[124:125], v[124:125], v[124:125]
	v_pk_fma_f32 v[118:119], v[118:119], v[118:119], v[120:121]
	v_pk_fma_f32 v[120:121], v[122:123], v[122:123], v[124:125]
	s_waitcnt vmcnt(16)
	v_and_b32_e32 v123, 0xffff0000, v103
	v_and_b32_e32 v133, 0xffff0000, v102
	v_lshlrev_b32_e32 v122, 16, v103
	v_lshlrev_b32_e32 v132, 16, v102
	v_mov_b32_e32 v124, v123
	v_mov_b32_e32 v125, v133
	v_mov_b32_e32 v102, v122
	v_mov_b32_e32 v103, v132
	v_pk_mul_f32 v[124:125], v[124:125], v[124:125]
	v_and_b32_e32 v135, 0xffff0000, v101
	v_and_b32_e32 v161, 0xffff0000, v100
	v_pk_fma_f32 v[102:103], v[102:103], v[102:103], v[124:125]
	v_lshlrev_b32_e32 v134, 16, v101
	v_lshlrev_b32_e32 v160, 16, v100
	v_mov_b32_e32 v124, v161
	v_mov_b32_e32 v125, v135
	v_mov_b32_e32 v100, v160
	v_mov_b32_e32 v101, v134
	v_pk_mul_f32 v[124:125], v[124:125], v[124:125]
	s_waitcnt vmcnt(0)
	v_lshlrev_b32_e32 v162, 16, v110
	v_pk_fma_f32 v[100:101], v[100:101], v[100:101], v[124:125]
	v_and_b32_e32 v163, 0xffff0000, v110
	v_pk_add_f32 v[100:101], v[100:101], v[100:101] op_sel:[0,1] op_sel_hi:[1,0]
	v_lshlrev_b32_e32 v110, 16, v109
	v_pk_add_f32 v[100:101], v[102:103], v[100:101] op_sel:[1,0] op_sel_hi:[0,1]
	v_pk_add_f32 v[100:101], v[102:103], v[100:101]
	v_lshlrev_b32_e32 v102, 16, v111
	v_and_b32_e32 v103, 0xffff0000, v111
	v_and_b32_e32 v111, 0xffff0000, v109
	v_and_b32_e32 v109, 0xffff0000, v107
	v_lshlrev_b32_e32 v164, 16, v108
	v_and_b32_e32 v165, 0xffff0000, v108
	v_lshlrev_b32_e32 v108, 16, v107
	v_and_b32_e32 v167, 0xffff0000, v106
	v_mov_b32_e32 v124, v109
	v_mov_b32_e32 v125, v103
	v_lshlrev_b32_e32 v166, 16, v106
	v_lshlrev_b32_e32 v106, 16, v105
	v_and_b32_e32 v107, 0xffff0000, v105
	v_lshlrev_b32_e32 v168, 16, v104
	v_and_b32_e32 v169, 0xffff0000, v104
	v_mov_b32_e32 v104, v108
	v_mov_b32_e32 v105, v102
	v_pk_mul_f32 v[124:125], v[124:125], v[124:125]
	v_mov_b32_e32 v158, v167
	v_mov_b32_e32 v159, v163
	v_pk_fma_f32 v[104:105], v[104:105], v[104:105], v[124:125]
	v_mov_b32_e32 v124, v166
	v_mov_b32_e32 v125, v162
	v_pk_mul_f32 v[158:159], v[158:159], v[158:159]
	v_mov_b32_e32 v170, v107
	v_mov_b32_e32 v171, v111
	v_pk_fma_f32 v[124:125], v[124:125], v[124:125], v[158:159]
	v_mov_b32_e32 v158, v106
	v_mov_b32_e32 v159, v110
	v_pk_mul_f32 v[170:171], v[170:171], v[170:171]
	v_mov_b32_e32 v172, v169
	v_mov_b32_e32 v173, v165
	v_pk_fma_f32 v[158:159], v[158:159], v[158:159], v[170:171]
	v_mov_b32_e32 v170, v168
	v_mov_b32_e32 v171, v164
	v_pk_mul_f32 v[172:173], v[172:173], v[172:173]
	v_pk_add_f32 v[120:121], v[120:121], v[120:121] op_sel:[0,1] op_sel_hi:[1,0]
	v_pk_fma_f32 v[170:171], v[170:171], v[170:171], v[172:173]
	v_and_b32_e32 v85, 0xffff0000, v92
	v_lshlrev_b32_e32 v86, 16, v91
	v_and_b32_e32 v87, 0xffff0000, v91
	v_and_b32_e32 v91, 0xffff0000, v99
	v_and_b32_e32 v95, 0xffff0000, v97
	v_and_b32_e32 v113, 0xffff0000, v96
	v_pk_add_f32 v[120:121], v[118:119], v[120:121] op_sel:[1,0] op_sel_hi:[0,1]
	v_pk_add_f32 v[158:159], v[170:171], v[158:159]
	v_lshlrev_b32_e32 v82, 16, v93
; __device__ __forceinline__ void xattn_fast(const Ctx& C) {
;     ...
;             for (int kk = 0; kk < 8; ++kk) { raw[kk] = *(const u32x4*)(qp + 16 * kk);
;                 const float a0 = bflo(raw[kk].x), a1 = bfhi(raw[kk].x), a2 = bflo(raw[kk].y), a3 = bfhi(raw[kk].y), a4 = bflo(raw[kk].z), a5 = bfhi(raw[kk].z), a6 = bflo(raw[kk].w), a7 = bfhi(raw[kk].w);
;                 ss += (a0 * a0 + a1 * a1) + (a2 * a2 + a3 * a3) + (a4 * a4 + a5 * a5) + (a6 * a6 + a7 * a7); }
;             { auto rr = __builtin_amdgcn_permlane32_swap(__float_as_uint(ss), __float_as_uint(ss), false, false); ss = __uint_as_float(rr[0]) + __uint_as_float(rr[1]); }
;             const float rq = rsqrtf(ss * (1.f / 128.f) + EPS) * XSCALE;
; #pragma unroll
;             for (int kk = 0; kk < 8; ++kk) {
;                 const f32x4 g0 = *(const f32x4*)(gq + 16 * kk + 8 * hf), g1 = *(const f32x4*)(gq + 16 * kk + 8 * hf + 4);
;                 qf[kk] = pack8(bflo(raw[kk].x) * rq * g0.x, bfhi(raw[kk].x) * rq * g0.y, bflo(raw[kk].y) * rq * g0.z, bfhi(raw[kk].y) * rq * g0.w,
;                                bflo(raw[kk].z) * rq * g1.x, bfhi(raw[kk].z) * rq * g1.y, bflo(raw[kk].w) * rq * g1.z, bfhi(raw[kk].w) * rq * g1.w);
;             }
	v_and_b32_e32 v83, 0xffff0000, v93
	v_lshlrev_b32_e32 v84, 16, v92
	v_lshlrev_b32_e32 v88, 16, v90
	v_and_b32_e32 v89, 0xffff0000, v90
	v_lshlrev_b32_e32 v90, 16, v99
	v_and_b32_e32 v93, 0xffff0000, v98
	v_lshlrev_b32_e32 v94, 16, v97
	v_lshlrev_b32_e32 v112, 16, v96
	v_mul_f32_e32 v130, v95, v95
	v_pk_add_f32 v[118:119], v[118:119], v[120:121]
	v_mul_f32_e32 v120, v113, v113
	v_pk_add_f32 v[124:125], v[124:125], v[158:159]
	v_mov_b32_e32 v158, v91
	v_mov_b32_e32 v159, v85
	v_lshlrev_b32_e32 v92, 16, v98
	v_pk_mul_f32 v[128:129], v[86:87], v[86:87]
	v_pk_fma_f32 v[130:131], v[94:95], v[94:95], v[130:131] op_sel_hi:[1,1,0]
	v_pk_fma_f32 v[120:121], v[112:113], v[112:113], v[120:121] op_sel_hi:[1,1,0]
	v_pk_add_f32 v[104:105], v[104:105], v[124:125]
	v_mov_b32_e32 v124, v90
	v_mov_b32_e32 v125, v84
	v_pk_mul_f32 v[158:159], v[158:159], v[158:159]
	v_mov_b32_e32 v170, v93
	v_mov_b32_e32 v171, v89
	v_pk_fma_f32 v[124:125], v[124:125], v[124:125], v[158:159]
	v_mov_b32_e32 v158, v92
	v_mov_b32_e32 v159, v88
	v_pk_mul_f32 v[170:171], v[170:171], v[170:171]
	v_mov_b32_e32 v121, v128
	v_mov_b32_e32 v131, v129
	v_pk_mul_f32 v[126:127], v[82:83], v[82:83]
	v_pk_add_f32 v[104:105], v[104:105], v[104:105] op_sel:[0,1] op_sel_hi:[1,0]
	v_pk_fma_f32 v[158:159], v[158:159], v[158:159], v[170:171]
	v_pk_add_f32 v[120:121], v[120:121], v[130:131]
	v_mov_b32_e32 v105, v126
	v_pk_add_f32 v[120:121], v[158:159], v[120:121]
	v_mov_b32_e32 v101, v127
	v_pk_add_f32 v[120:121], v[124:125], v[120:121]
	v_pk_add_f32 v[100:101], v[104:105], v[100:101]
	v_mov_b32_e32 v104, v64
	v_pk_add_f32 v[100:101], v[100:101], v[120:121]
	v_mov_b32_e32 v120, v65
	v_mov_b32_e32 v121, v59
	v_mov_b32_e32 v105, v58
	v_pk_mul_f32 v[120:121], v[120:121], v[120:121]
	v_mov_b32_e32 v124, v67
	v_mov_b32_e32 v125, v63
	v_pk_fma_f32 v[104:105], v[104:105], v[104:105], v[120:121]
	v_mov_b32_e32 v120, v66
	v_mov_b32_e32 v121, v62
	v_pk_mul_f32 v[124:125], v[124:125], v[124:125]
	v_mul_f32_e32 v114, v69, v69
	v_pk_fma_f32 v[120:121], v[120:121], v[120:121], v[124:125]
	global_load_dwordx4 v[124:127], v[152:153], off offset:464
	global_load_dwordx4 v[128:131], v[152:153], off offset:448
	v_mul_f32_e32 v116, v71, v71
	v_pk_mul_f32 v[98:99], v[60:61], v[60:61]
	v_pk_fma_f32 v[114:115], v[68:69], v[68:69], v[114:115] op_sel_hi:[1,1,0]
	v_pk_fma_f32 v[116:117], v[70:71], v[70:71], v[116:117] op_sel_hi:[1,1,0]
	v_mov_b32_e32 v115, v99
	v_mov_b32_e32 v117, v98
	v_pk_mul_f32 v[96:97], v[56:57], v[56:57]
	v_pk_add_f32 v[100:101], v[100:101], v[100:101] op_sel:[0,1] op_sel_hi:[1,0]
	v_pk_add_f32 v[98:99], v[116:117], v[114:115]
	v_mov_b32_e32 v101, v96
	v_pk_add_f32 v[98:99], v[120:121], v[98:99]
	v_mov_b32_e32 v119, v97
	v_pk_add_f32 v[98:99], v[104:105], v[98:99]
	v_pk_add_f32 v[96:97], v[100:101], v[118:119]
	v_lshlrev_b64 v[158:159], 9, v[80:81]
	v_pk_add_f32 v[96:97], v[96:97], v[98:99]
	s_nop 0
	v_pk_add_f32 v[96:97], v[96:97], v[96:97] op_sel:[0,1] op_sel_hi:[1,0]
	s_nop 0
	v_mov_b32_e32 v97, v96
	s_nop 1
	v_permlane32_swap_b32_e32 v96, v97
	v_add_f32_e32 v96, v96, v97
	v_fmamk_f32 v96, v96, 0x3c000000, v143
	v_mul_f32_e32 v97, 0x4b800000, v96
	v_cmp_gt_f32_e32 vcc, s0, v96
	s_nop 1
	v_cndmask_b32_e32 v96, v96, v97, vcc
	v_rsq_f32_e32 v96, v96
	s_nop 0
	v_mul_f32_e32 v80, 0x45800000, v96
	v_cndmask_b32_e32 v80, v96, v80, vcc
	v_mul_f32_e32 v80, 0x3e0293ee, v80
	v_pk_mul_f32 v[96:97], v[80:81], v[168:169] op_sel_hi:[0,1]
	v_pk_mul_f32 v[52:53], v[52:53], v[96:97]
	v_pk_mul_f32 v[96:97], v[80:81], v[106:107] op_sel_hi:[0,1]
	v_pk_mul_f32 v[54:55], v[54:55], v[96:97]
	v_pk_mul_f32 v[96:97], v[80:81], v[166:167] op_sel_hi:[0,1]
	v_pk_mul_f32 v[48:49], v[48:49], v[96:97]
	v_pk_mul_f32 v[96:97], v[80:81], v[108:109] op_sel_hi:[0,1]
	v_cvt_pk_bf16_f32 v98, v48, v49
	v_pk_mul_f32 v[48:49], v[80:81], v[164:165] op_sel_hi:[0,1]
	v_pk_mul_f32 v[44:45], v[44:45], v[48:49]
	v_pk_mul_f32 v[48:49], v[80:81], v[110:111] op_sel_hi:[0,1]
	v_pk_mul_f32 v[46:47], v[46:47], v[48:49]
	v_pk_mul_f32 v[48:49], v[80:81], v[162:163] op_sel_hi:[0,1]
	v_pk_mul_f32 v[40:41], v[40:41], v[48:49]
	v_pk_mul_f32 v[48:49], v[80:81], v[102:103] op_sel_hi:[0,1]
	v_cvt_pk_bf16_f32 v102, v40, v41
	v_pk_mul_f32 v[40:41], v[80:81], v[160:161] op_sel_hi:[0,1]
	v_pk_mul_f32 v[36:37], v[36:37], v[40:41]
	v_pk_mul_f32 v[40:41], v[80:81], v[134:135] op_sel_hi:[0,1]
	v_pk_mul_f32 v[38:39], v[38:39], v[40:41]
	v_pk_mul_f32 v[40:41], v[80:81], v[132:133] op_sel_hi:[0,1]
	v_pk_mul_f32 v[32:33], v[32:33], v[40:41]
	v_pk_mul_f32 v[40:41], v[80:81], v[122:123] op_sel_hi:[0,1]
	v_cvt_pk_bf16_f32 v106, v32, v33
	v_pk_mul_f32 v[32:33], v[80:81], v[112:113] op_sel_hi:[0,1]
	v_pk_mul_f32 v[28:29], v[28:29], v[32:33]
	v_pk_mul_f32 v[32:33], v[80:81], v[94:95] op_sel_hi:[0,1]
	v_pk_mul_f32 v[30:31], v[30:31], v[32:33]
	v_pk_mul_f32 v[32:33], v[80:81], v[92:93] op_sel_hi:[0,1]
	v_pk_mul_f32 v[24:25], v[24:25], v[32:33]
	v_pk_mul_f32 v[32:33], v[80:81], v[90:91] op_sel_hi:[0,1]
	v_cvt_pk_bf16_f32 v110, v24, v25
	v_pk_mul_f32 v[24:25], v[80:81], v[88:89] op_sel_hi:[0,1]
	v_pk_mul_f32 v[20:21], v[20:21], v[24:25]
	v_pk_mul_f32 v[24:25], v[80:81], v[86:87] op_sel_hi:[0,1]
	v_pk_mul_f32 v[22:23], v[22:23], v[24:25]
	v_pk_mul_f32 v[24:25], v[80:81], v[84:85] op_sel_hi:[0,1]
	v_pk_mul_f32 v[16:17], v[16:17], v[24:25]
	v_pk_mul_f32 v[24:25], v[80:81], v[82:83] op_sel_hi:[0,1]
	v_cvt_pk_bf16_f32 v114, v16, v17
	v_pk_mul_f32 v[16:17], v[80:81], v[78:79] op_sel_hi:[0,1]
	v_pk_mul_f32 v[12:13], v[12:13], v[16:17]
	v_pk_mul_f32 v[16:17], v[80:81], v[76:77] op_sel_hi:[0,1]
	v_pk_mul_f32 v[14:15], v[14:15], v[16:17]
	v_pk_mul_f32 v[16:17], v[80:81], v[74:75] op_sel_hi:[0,1]
	v_pk_mul_f32 v[8:9], v[16:17], v[8:9]
	v_pk_mul_f32 v[16:17], v[80:81], v[72:73] op_sel_hi:[0,1]
	v_cvt_pk_bf16_f32 v118, v8, v9
	v_pk_mul_f32 v[8:9], v[80:81], v[70:71] op_sel_hi:[0,1]
	v_pk_mul_f32 v[4:5], v[8:9], v[4:5]
	v_pk_mul_f32 v[8:9], v[80:81], v[68:69] op_sel_hi:[0,1]
	v_pk_mul_f32 v[6:7], v[8:9], v[6:7]
	v_pk_mul_f32 v[8:9], v[80:81], v[66:67] op_sel_hi:[0,1]
	v_pk_mul_f32 v[0:1], v[8:9], v[0:1]
	v_pk_mul_f32 v[8:9], v[80:81], v[64:65] op_sel_hi:[0,1]
	v_pk_mul_f32 v[2:3], v[8:9], v[2:3]
	v_cvt_pk_bf16_f32 v120, v4, v5
	v_cvt_pk_bf16_f32 v121, v6, v7
	v_cvt_pk_bf16_f32 v122, v0, v1
	v_cvt_pk_bf16_f32 v123, v2, v3
	v_pk_mul_f32 v[0:1], v[80:81], v[62:63] op_sel_hi:[0,1]
	v_pk_mul_f32 v[2:3], v[80:81], v[60:61] op_sel_hi:[0,1]
	v_pk_mul_f32 v[4:5], v[80:81], v[58:59] op_sel_hi:[0,1]
	v_pk_mul_f32 v[6:7], v[80:81], v[56:57] op_sel_hi:[0,1]
	v_pk_mul_f32 v[50:51], v[50:51], v[96:97]
	v_pk_mul_f32 v[42:43], v[42:43], v[48:49]
	v_pk_mul_f32 v[34:35], v[34:35], v[40:41]
	v_pk_mul_f32 v[26:27], v[26:27], v[32:33]
	v_pk_mul_f32 v[18:19], v[18:19], v[24:25]
	v_pk_mul_f32 v[10:11], v[16:17], v[10:11]
	s_waitcnt vmcnt(0)
; __device__ __forceinline__ void xattn_fast(const Ctx& C) {
;     ...
;             for (int kk = 0; kk < 8; ++kk) {
;                 const f32x4 g0 = *(const f32x4*)(gq + 16 * kk + 8 * hf), g1 = *(const f32x4*)(gq + 16 * kk + 8 * hf + 4);
;                 qf[kk] = pack8(bflo(raw[kk].x) * rq * g0.x, bfhi(raw[kk].x) * rq * g0.y, bflo(raw[kk].y) * rq * g0.z, bfhi(raw[kk].y) * rq * g0.w,
;                                bflo(raw[kk].z) * rq * g1.x, bfhi(raw[kk].z) * rq * g1.y, bflo(raw[kk].w) * rq * g1.z, bfhi(raw[kk].w) * rq * g1.w);
;             }
;         }
;         f32x16 o[4];
; #pragma unroll
;         for (int mb = 0; mb < 4; ++mb)
; #pragma unroll
;             for (int r = 0; r < 16; ++r) o[mb][r] = 0.f;
	v_pk_mul_f32 v[0:1], v[0:1], v[128:129]
	v_pk_mul_f32 v[2:3], v[2:3], v[130:131]
	v_pk_mul_f32 v[4:5], v[4:5], v[124:125]
	v_pk_mul_f32 v[6:7], v[6:7], v[126:127]
	v_mov_b32_e32 v161, 0
	v_cvt_pk_bf16_f32 v96, v52, v53
	v_cvt_pk_bf16_f32 v97, v54, v55
	v_cvt_pk_bf16_f32 v99, v50, v51
	v_cvt_pk_bf16_f32 v100, v44, v45
	v_cvt_pk_bf16_f32 v101, v46, v47
	v_cvt_pk_bf16_f32 v103, v42, v43
	v_cvt_pk_bf16_f32 v104, v36, v37
	v_cvt_pk_bf16_f32 v105, v38, v39
	v_cvt_pk_bf16_f32 v107, v34, v35
	v_cvt_pk_bf16_f32 v108, v28, v29
	v_cvt_pk_bf16_f32 v109, v30, v31
	v_cvt_pk_bf16_f32 v111, v26, v27
	v_cvt_pk_bf16_f32 v112, v20, v21
	v_cvt_pk_bf16_f32 v113, v22, v23
	v_cvt_pk_bf16_f32 v115, v18, v19
	v_cvt_pk_bf16_f32 v116, v12, v13
	v_cvt_pk_bf16_f32 v117, v14, v15
	v_cvt_pk_bf16_f32 v119, v10, v11
	v_cvt_pk_bf16_f32 v124, v0, v1
	v_cvt_pk_bf16_f32 v125, v2, v3
	v_cvt_pk_bf16_f32 v126, v4, v5
	v_cvt_pk_bf16_f32 v127, v6, v7
	v_mov_b32_e32 v0, 0
	v_mov_b32_e32 v1, v161
	v_mov_b32_e32 v2, v161
	v_mov_b32_e32 v3, v161
	v_mov_b32_e32 v4, v161
	v_mov_b32_e32 v5, v161
	v_mov_b32_e32 v6, v161
	v_mov_b32_e32 v7, v161
	v_mov_b32_e32 v8, v161
	v_mov_b32_e32 v9, v161
	v_mov_b32_e32 v10, v161
	v_mov_b32_e32 v11, v161
	v_mov_b32_e32 v12, v161
	v_mov_b32_e32 v13, v161
	v_mov_b32_e32 v14, v161
	v_mov_b32_e32 v15, v161
	v_mov_b32_e32 v16, 0
	v_mov_b32_e32 v17, v161
	v_mov_b32_e32 v18, v161
	v_mov_b32_e32 v19, v161
	v_mov_b32_e32 v20, v161
	v_mov_b32_e32 v21, v161
	v_mov_b32_e32 v22, v161
	v_mov_b32_e32 v23, v161
	v_mov_b32_e32 v24, v161
	v_mov_b32_e32 v25, v161
	v_mov_b32_e32 v26, v161
	v_mov_b32_e32 v27, v161
	v_mov_b32_e32 v28, v161
	v_mov_b32_e32 v29, v161
	v_mov_b32_e32 v30, v161
	v_mov_b32_e32 v31, v161
	v_mov_b32_e32 v32, 0
	v_mov_b32_e32 v33, v161
	v_mov_b32_e32 v34, v161
	v_mov_b32_e32 v35, v161
	v_mov_b32_e32 v36, v161
	v_mov_b32_e32 v37, v161
	v_mov_b32_e32 v38, v161
	v_mov_b32_e32 v39, v161
	v_mov_b32_e32 v40, v161
	v_mov_b32_e32 v41, v161
	v_mov_b32_e32 v42, v161
	v_mov_b32_e32 v43, v161
	v_mov_b32_e32 v44, v161
	v_mov_b32_e32 v45, v161
	v_mov_b32_e32 v46, v161
	v_mov_b32_e32 v47, v161
	v_mov_b32_e32 v48, 0
	v_mov_b32_e32 v49, v161
	v_mov_b32_e32 v50, v161
	v_mov_b32_e32 v51, v161
	v_mov_b32_e32 v52, v161
	v_mov_b32_e32 v53, v161
	v_mov_b32_e32 v54, v161
	v_mov_b32_e32 v55, v161
	v_mov_b32_e32 v56, v161
	v_mov_b32_e32 v57, v161
	v_mov_b32_e32 v58, v161
	v_mov_b32_e32 v59, v161
	v_mov_b32_e32 v60, v161
	v_mov_b32_e32 v61, v161
	v_mov_b32_e32 v62, v161
	v_mov_b32_e32 v63, v161
